# v59 + layer-2 filter tiles 248..367 computed in the idle sixth round of layer 1's FFN-up GEMM (WGs 216..255, 3 tiles each); layer 2's k0 keeps one tile per WG
# baseline (speedup 1.0000x reference)
.LBB0_148:
	s_waitcnt vmcnt(0)
	v_readlane_b32 s28, v255, 4
	v_readlane_b32 s36, v255, 6
	v_readlane_b32 s70, v255, 8
	v_readlane_b32 s74, v255, 10
	v_readlane_b32 s50, v255, 36
	v_readlane_b32 s29, v255, 5
	v_readlane_b32 s37, v255, 7
	v_readlane_b32 s71, v255, 9
	v_readlane_b32 s75, v255, 11
	s_movk_i32 s77, 0x60
	v_readlane_b32 s51, v255, 37
	s_barrier
	s_cmp_eq_u32 s56, 0x100
	s_cbranch_scc0 .LBB0_149
	s_cmp_eq_u32 s62, 15
	s_cbranch_scc0 .LBB0_149
	s_cmp_lt_u32 s96, 0xd8
	s_cbranch_scc1 .LBB0_149
	s_mov_b64 s[0:1], s[72:73]
	s_load_dwordx2 s[64:65], s[72:73], 0x120
	s_mov_b32 s98, 1
	s_mov_b32 s99, 0
	s_nop 3
	v_writelane_b32 v255, s98, 29
	v_writelane_b32 v255, s99, 30
	s_add_i32 s101, s96, 32
	s_movk_i32 s98, 40
	s_movk_i32 s99, 0x16f
	s_waitcnt lgkmcnt(0)
	s_branch .Lkt_entry
	s_nop 0
	s_nop 0
	s_nop 0
	s_nop 0
	s_nop 0
	s_nop 0
	s_nop 0
	s_nop 0
	s_nop 0

.LBB0_562:
	v_readlane_b32 s2, v253, 16
	v_readlane_b32 s6, v255, 22
	v_readlane_b32 s3, v253, 17
	v_readlane_b32 s7, v255, 23
	s_or_b64 s[2:3], s[6:7], s[2:3]
	s_and_b64 vcc, exec, s[2:3]
	s_cbranch_vccnz .LBB0_567
	s_mov_b32 s101, s96
	s_mov_b32 s98, s56
	s_movk_i32 s99, 0x21f
	s_cmp_eq_u32 s56, 0x100
	s_cbranch_scc0 .Lkt_entry
	s_movk_i32 s99, 0x16f
	v_readlane_b32 s100, v255, 29
	s_cmp_eq_u32 s100, 1
	s_cbranch_scc0 .Lkt_entry
	s_movk_i32 s99, 0xf7
